# v14 + attention pass prologue: tile-0 and tile-1 K/V loads issued together before the barrier
# speedup vs baseline: 1.0008x; 1.0008x over previous
; template <int PM> DI void attn_phase(const Params& p, int l, char* smem, int* s_item, int wv, int cidx) {
;     ...
;       u32x4 kst[2], vst[2];
;       __syncthreads();
;       {
;         const u16* base = p.P + (size_t)(Rb + trow) * INW + tch * 8;
; #pragma unroll
;         for (int j = 0; j < 2; ++j) {
;           kst[j] = *(const u32x4*)(base + (size_t)j * 32 * INW + koff);
;           vst[j] = *(const u32x4*)(base + (size_t)j * 32 * INW + voff);
;         }
; #pragma unroll
;         for (int j = 0; j < 2; ++j) {
;           *(u32x4*)(Kb0 + (trow + 32 * j) * 272 + tch * 16) = kst[j];
;           *(u32x4*)(Vb0 + (trow + 32 * j) * 320 + tch * 16) = vst[j];
;         }
;         const int R1 = (1 < nplain) ? Rb + 64 : Rb + 256 + local_t0 + 64 * (1 - nplain);
;         const u16* b1 = p.P + (size_t)(R1 + trow) * INW + tch * 8;
;         if (ntl > 1) {
; #pragma unroll
;           for (int j = 0; j < 2; ++j) {
;             kst[j] = *(const u32x4*)(b1 + (size_t)j * 32 * INW + koff);
;             vst[j] = *(const u32x4*)(b1 + (size_t)j * 32 * INW + voff);
;           }
;         }
;       }
.LBB0_418:
	global_load_dwordx4 v[180:183], v[210:211], off
	global_load_dwordx4 v[184:187], v[212:213], off
	global_load_dwordx4 v[188:191], v[214:215], off
	global_load_dwordx4 v[192:195], v[216:217], off
	v_readlane_b32 s0, v255, 1
	v_readlane_b32 s1, v255, 2
	v_add_u32_e32 v0, v196, v246
	v_add_u32_e32 v2, v196, v247
	s_andn2_b64 vcc, exec, s[0:1]
	s_cbranch_vccnz .Lpp_not1
	global_load_dwordx4 v[80:83], v[224:225], off
	global_load_dwordx4 v[84:87], v[222:223], off
	global_load_dwordx4 v[88:91], v[220:221], off
	global_load_dwordx4 v[92:95], v[218:219], off
.Lpp_not1:
	s_waitcnt lgkmcnt(0)
	s_barrier
	s_waitcnt vmcnt(0)
	ds_write_b128 v0, v[180:183]
	ds_write_b128 v2, v[184:187] offset:34816
	ds_write_b128 v0, v[188:191] offset:8704
	ds_write_b128 v2, v[192:195] offset:45056
	s_cbranch_vccnz .LBB0_420
	s_waitcnt lgkmcnt(0)
	v_mov_b64_e32 v[180:181], v[80:81]
	v_mov_b64_e32 v[182:183], v[82:83]
	v_mov_b64_e32 v[184:185], v[84:85]
	v_mov_b64_e32 v[186:187], v[86:87]
	v_mov_b64_e32 v[188:189], v[88:89]
	v_mov_b64_e32 v[190:191], v[90:91]
	v_mov_b64_e32 v[192:193], v[92:93]
	v_mov_b64_e32 v[194:195], v[94:95]
